# FFN-in paired tiles: the tile prologue no longer drains the first stage's LDS-DMA before issuing the second tile's and the next weight stage's loads
# baseline (speedup 1.0000x reference)
; #define LAS __attribute__((address_space(3)))
; DI int opaque_tid() { int t = threadIdx.x; asm volatile("" : "+v"(t)); return t; }
; template <class Epi>
; DI void gemm_tile(const bf16_t* __restrict__ A, int lda, const bf16_t* __restrict__ Bt, int ldb, int K, int row0, int col0, char* lds, const Epi& epi) {
;   const int tid = opaque_tid(), lane = tid & 63, wid = tid >> 6, wr = wid >> 1, wc = wid & 1, fr = lane & 15, fq = lane >> 4;
;   const bf16_t* ag[4];
;   const bf16_t* bg[4];
; #pragma unroll
;   for (int i = 0; i < 4; ++i) {
;     const int id = i * 256 + tid, r = id >> 3, cp = id & 7, c = cp ^ ((r >> 1) & 7);
;     ag[i] = A + (size_t)(row0 + r) * lda + c * 8;
;     bg[i] = Bt + (size_t)(col0 + r) * ldb + c * 8;
;   }
;   f32x4 acc[4][4];
; #pragma unroll
;   for (int m = 0; m < 4; ++m)
; #pragma unroll
;     for (int n = 0; n < 4; ++n) acc[m][n] = (f32x4){0.f, 0.f, 0.f, 0.f};
;   const int KT = K >> 6;
;   auto stage_a = [&](int kt, int buf) {
;     char* sa = lds + buf * 32768;
; #pragma unroll
;     for (int i = 0; i < 4; ++i)
;       __builtin_amdgcn_global_load_lds((const void __attribute__((address_space(1)))*)(ag[i] + kt * 64), (void LAS*)(sa + (i * 256 + tid) * 16), 16, 0, 0);
;   };
;   auto stage_b = [&](int kt, int buf) {
;     char* sb = lds + buf * 32768 + 16384;
; #pragma unroll
;     for (int i = 0; i < 4; ++i)
;       __builtin_amdgcn_global_load_lds((const void __attribute__((address_space(1)))*)(bg[i] + kt * 64), (void LAS*)(sb + (i * 256 + tid) * 16), 16, 0, 0);
;   };
;   __syncthreads();
;   stage_a(0, 0); stage_b(0, 0);
;   const int swz = fr >> 1;
.LBB0_135:
	v_mov_b32_e32 v34, v138
	s_lshl_b32 s2, s28, 7
	v_lshrrev_b32_e32 v35, 4, v34
	v_xor_b32_e32 v1, v35, v34
	v_lshlrev_b32_e32 v1, 4, v1
	s_lshl_b32 s3, s29, 7
	v_and_b32_e32 v110, 0x70, v1
	v_ashrrev_i32_e32 v1, 3, v34
	v_add_u32_e32 v6, s2, v1
	v_add_u32_e32 v10, s3, v1
	v_add_u32_e32 v1, 0x100, v34
	v_readlane_b32 s4, v253, 36
	v_ashrrev_i32_e32 v1, 3, v1
	v_readlane_b32 s8, v253, 40
	v_readlane_b32 s9, v253, 41
	v_ashrrev_i32_e32 v7, 31, v6
	v_add_u32_e32 v14, s2, v1
	v_add_u32_e32 v18, s3, v1
	v_add_u32_e32 v1, 0x200, v34
	s_waitcnt vmcnt(6)
	v_lshlrev_b32_e32 v92, 4, v34
	v_lshl_add_u64 v[2:3], s[8:9], 0, v[110:111]
	v_lshlrev_b64 v[6:7], 11, v[6:7]
	v_ashrrev_i32_e32 v1, 3, v1
	v_readfirstlane_b32 s0, v92
	v_lshl_add_u64 v[8:9], v[2:3], 0, v[6:7]
	v_add_u32_e32 v22, s2, v1
	v_add_u32_e32 v26, s3, v1
	v_add_u32_e32 v1, 0x300, v34
	s_mov_b32 m0, s0
	v_ashrrev_i32_e32 v15, 31, v14
	v_ashrrev_i32_e32 v1, 3, v1
	s_barrier
	global_load_lds_dwordx4 v[8:9], off
	v_add_u32_e32 v8, 0x1000, v92
	v_lshlrev_b64 v[14:15], 11, v[14:15]
	v_ashrrev_i32_e32 v23, 31, v22
	v_add_u32_e32 v30, s2, v1
	v_readfirstlane_b32 s0, v8
	v_add_u32_e32 v8, 0x2000, v92
	v_lshl_add_u64 v[16:17], v[2:3], 0, v[14:15]
	v_lshlrev_b64 v[22:23], 11, v[22:23]
	v_ashrrev_i32_e32 v31, 31, v30
	s_mov_b32 m0, s0
	v_readfirstlane_b32 s0, v8
	v_add_u32_e32 v8, 0x3000, v92
	v_lshl_add_u64 v[24:25], v[2:3], 0, v[22:23]
	v_lshlrev_b64 v[30:31], 11, v[30:31]
	global_load_lds_dwordx4 v[16:17], off
	s_mov_b32 m0, s0
	v_readfirstlane_b32 s0, v8
	v_lshl_add_u64 v[2:3], v[2:3], 0, v[30:31]
	global_load_lds_dwordx4 v[24:25], off
	s_mov_b32 m0, s0
	v_readlane_b32 s5, v253, 37
	v_ashrrev_i32_e32 v11, 31, v10
	global_load_lds_dwordx4 v[2:3], off
	v_add_u32_e32 v2, 0x4000, v92
	v_lshl_add_u64 v[4:5], s[4:5], 0, v[110:111]
	v_lshlrev_b64 v[10:11], 11, v[10:11]
	v_ashrrev_i32_e32 v19, 31, v18
	v_readfirstlane_b32 s0, v2
	v_add_u32_e32 v2, 0x5000, v92
	v_lshl_add_u64 v[12:13], v[4:5], 0, v[10:11]
	v_lshlrev_b64 v[18:19], 11, v[18:19]
	v_ashrrev_i32_e32 v27, 31, v26
	v_add_u32_e32 v32, s3, v1
	s_mov_b32 m0, s0
	v_readfirstlane_b32 s0, v2
	v_add_u32_e32 v2, 0x6000, v92
	v_lshl_add_u64 v[20:21], v[4:5], 0, v[18:19]
	v_lshlrev_b64 v[26:27], 11, v[26:27]
	v_ashrrev_i32_e32 v33, 31, v32
	global_load_lds_dwordx4 v[12:13], off
	s_mov_b32 m0, s0
	v_readfirstlane_b32 s0, v2
	v_add_u32_e32 v2, 0x7000, v92
	v_lshl_add_u64 v[28:29], v[4:5], 0, v[26:27]
	v_lshlrev_b64 v[32:33], 11, v[32:33]
	global_load_lds_dwordx4 v[20:21], off
	s_mov_b32 m0, s0
	v_readfirstlane_b32 s0, v2
	v_lshl_add_u64 v[4:5], v[4:5], 0, v[32:33]
	global_load_lds_dwordx4 v[28:29], off
	s_mov_b32 m0, s0
	v_and_b32_e32 v87, 15, v34
	global_load_lds_dwordx4 v[4:5], off
	v_bfe_u32 v86, v34, 6, 1
	v_ashrrev_i32_e32 v88, 7, v34
	v_bfe_u32 v1, v34, 4, 2
	v_bfe_u32 v2, v34, 1, 3
	v_lshlrev_b32_e32 v3, 7, v87
	v_lshl_or_b32 v89, v88, 13, v3
	v_lshl_or_b32 v91, v86, 13, v3
	v_bitop3_b32 v3, v1, v2, 4 bitop3:0x36
	v_bitop3_b32 v2, v35, v2, 3 bitop3:0x6c
	v_lshlrev_b32_e32 v93, 4, v2
	v_bitop3_b32 v2, v35, 7, v34 bitop3:0x48
	v_lshlrev_b32_e32 v2, 4, v2
	v_readlane_b32 s0, v253, 13
	v_or_b32_e32 v10, v10, v2
	v_readlane_b32 s1, v253, 14
	v_or_b32_e32 v18, v18, v2
	v_or_b32_e32 v26, v26, v2
	v_or_b32_e32 v32, v32, v2
	s_nop 0
	v_lshl_add_u64 v[66:67], s[0:1], 0, v[10:11]
	v_lshl_add_u64 v[68:69], s[0:1], 0, v[18:19]
	v_lshl_add_u64 v[70:71], s[0:1], 0, v[26:27]
	v_lshl_add_u64 v[72:73], s[0:1], 0, v[32:33]
	v_readlane_b32 s0, v254, 60
	v_or_b32_e32 v6, v6, v2
	v_readlane_b32 s1, v254, 61
	v_or_b32_e32 v14, v14, v2
	v_or_b32_e32 v22, v22, v2
	v_or_b32_e32 v30, v30, v2
	v_mov_b32_e32 v2, 0
	v_lshlrev_b32_e32 v90, 4, v3
	v_lshl_add_u64 v[74:75], s[0:1], 0, v[6:7]
	v_lshl_add_u64 v[76:77], s[0:1], 0, v[14:15]
	v_lshl_add_u64 v[78:79], s[0:1], 0, v[22:23]
	v_lshl_add_u64 v[80:81], s[0:1], 0, v[30:31]
	s_mov_b64 s[0:1], 0
	s_mov_b32 s28, 0x8000
	v_mov_b32_e32 v3, v2
	v_mov_b32_e32 v4, v2
	v_mov_b32_e32 v5, v2
	v_mov_b32_e32 v6, v2
	v_mov_b32_e32 v7, v2
	v_mov_b32_e32 v8, v2
	v_mov_b32_e32 v9, v2
	v_mov_b32_e32 v10, v2
	v_mov_b32_e32 v11, v2
	v_mov_b32_e32 v12, v2
; #define LAS __attribute__((address_space(3)))
; template <class Epi>
; DI void gemm_tile(const bf16_t* __restrict__ A, int lda, const bf16_t* __restrict__ Bt, int ldb, int K, int row0, int col0, char* lds, const Epi& epi) {
;     ...
;   f32x4 acc[4][4];
; #pragma unroll
;   for (int m = 0; m < 4; ++m)
; #pragma unroll
;     for (int n = 0; n < 4; ++n) acc[m][n] = (f32x4){0.f, 0.f, 0.f, 0.f};
;   const int KT = K >> 6;
;   auto stage_a = [&](int kt, int buf) {
;     char* sa = lds + buf * 32768;
; #pragma unroll
;     for (int i = 0; i < 4; ++i)
;       __builtin_amdgcn_global_load_lds((const void __attribute__((address_space(1)))*)(ag[i] + kt * 64), (void LAS*)(sa + (i * 256 + tid) * 16), 16, 0, 0);
;   };
;   auto stage_b = [&](int kt, int buf) {
;     char* sb = lds + buf * 32768 + 16384;
; #pragma unroll
;     for (int i = 0; i < 4; ++i)
;       __builtin_amdgcn_global_load_lds((const void __attribute__((address_space(1)))*)(bg[i] + kt * 64), (void LAS*)(sb + (i * 256 + tid) * 16), 16, 0, 0);
;   };
;   __syncthreads();
;   stage_a(0, 0); stage_b(0, 0);
;   const int swz = fr >> 1;
	v_mov_b32_e32 v13, v2
	v_mov_b32_e32 v14, v2
	v_mov_b32_e32 v15, v2
	v_mov_b32_e32 v16, v2
	v_mov_b32_e32 v17, v2
	v_mov_b32_e32 v18, v2
	v_mov_b32_e32 v19, v2
	v_mov_b32_e32 v20, v2
	v_mov_b32_e32 v21, v2
	v_mov_b32_e32 v22, v2
	v_mov_b32_e32 v23, v2
	v_mov_b32_e32 v24, v2
	v_mov_b32_e32 v25, v2
	v_mov_b32_e32 v26, v2
	v_mov_b32_e32 v27, v2
	v_mov_b32_e32 v28, v2
	v_mov_b32_e32 v29, v2
	v_mov_b32_e32 v30, v2
	v_mov_b32_e32 v31, v2
	v_mov_b32_e32 v32, v2
	v_mov_b32_e32 v33, v2
	v_mov_b32_e32 v34, v2
	v_mov_b32_e32 v35, v2
	v_mov_b32_e32 v36, v2
	v_mov_b32_e32 v37, v2
	v_mov_b32_e32 v38, v2
	v_mov_b32_e32 v39, v2
	v_mov_b32_e32 v40, v2
	v_mov_b32_e32 v41, v2
	v_mov_b32_e32 v42, v2
	v_mov_b32_e32 v43, v2
	v_mov_b32_e32 v44, v2
	v_mov_b32_e32 v45, v2
	v_mov_b32_e32 v46, v2
	v_mov_b32_e32 v47, v2
	v_mov_b32_e32 v48, v2
	v_mov_b32_e32 v49, v2
	v_mov_b32_e32 v50, v2
	v_mov_b32_e32 v51, v2
	v_mov_b32_e32 v52, v2
	v_mov_b32_e32 v53, v2
	v_mov_b32_e32 v54, v2
	v_mov_b32_e32 v55, v2
	v_mov_b32_e32 v56, v2
	v_mov_b32_e32 v57, v2
	v_mov_b32_e32 v58, v2
	v_mov_b32_e32 v59, v2
	v_mov_b32_e32 v60, v2
	v_mov_b32_e32 v61, v2
	v_mov_b32_e32 v62, v2
	v_mov_b32_e32 v63, v2
	v_mov_b32_e32 v64, v2
	v_mov_b32_e32 v65, v2
	v_readlane_b32 s6, v253, 38
	v_readlane_b32 s7, v253, 39
	v_readlane_b32 s10, v253, 42
	v_readlane_b32 s11, v253, 43
	v_readlane_b32 s12, v253, 44
	v_readlane_b32 s13, v253, 45
	v_readlane_b32 s14, v253, 46
	v_readlane_b32 s15, v253, 47
	v_readlane_b32 s16, v253, 48
	v_readlane_b32 s17, v253, 49
	v_readlane_b32 s18, v253, 50
	v_readlane_b32 s19, v253, 51
	v_mov_b32_e32 v162, 0
	v_mov_b32_e32 v163, 0
	v_mov_b32_e32 v164, 0
	v_mov_b32_e32 v165, 0
	v_mov_b32_e32 v166, 0
	v_mov_b32_e32 v167, 0
	v_mov_b32_e32 v168, 0
	v_mov_b32_e32 v169, 0
	v_mov_b32_e32 v170, 0
	v_mov_b32_e32 v171, 0
	v_mov_b32_e32 v172, 0
	v_mov_b32_e32 v173, 0
	v_mov_b32_e32 v174, 0
	v_mov_b32_e32 v175, 0
	v_mov_b32_e32 v176, 0
	v_mov_b32_e32 v177, 0
	v_mov_b32_e32 v178, 0
	v_mov_b32_e32 v179, 0
	v_mov_b32_e32 v180, 0
	v_mov_b32_e32 v181, 0
	v_mov_b32_e32 v182, 0
	v_mov_b32_e32 v183, 0
	v_mov_b32_e32 v184, 0
	v_mov_b32_e32 v185, 0
	v_mov_b32_e32 v186, 0
	v_mov_b32_e32 v187, 0
	v_mov_b32_e32 v188, 0
	v_mov_b32_e32 v189, 0
	v_mov_b32_e32 v190, 0
	v_mov_b32_e32 v191, 0
	v_mov_b32_e32 v192, 0
	v_mov_b32_e32 v193, 0
	v_mov_b32_e32 v194, 0
	v_mov_b32_e32 v195, 0
	v_mov_b32_e32 v196, 0
	v_mov_b32_e32 v197, 0
	v_mov_b32_e32 v198, 0
	v_mov_b32_e32 v199, 0
	v_mov_b32_e32 v200, 0
	v_mov_b32_e32 v201, 0
	v_mov_b32_e32 v202, 0
	v_mov_b32_e32 v203, 0
	v_mov_b32_e32 v204, 0
	v_mov_b32_e32 v205, 0
	v_mov_b32_e32 v206, 0
	v_mov_b32_e32 v207, 0
	v_mov_b32_e32 v208, 0
	v_mov_b32_e32 v209, 0
	v_mov_b32_e32 v210, 0
	v_mov_b32_e32 v211, 0
	v_mov_b32_e32 v212, 0
	v_mov_b32_e32 v213, 0
	v_mov_b32_e32 v214, 0
	v_mov_b32_e32 v215, 0
	v_mov_b32_e32 v216, 0
	v_mov_b32_e32 v217, 0
	v_mov_b32_e32 v218, 0
	v_mov_b32_e32 v219, 0
	v_mov_b32_e32 v220, 0
	v_mov_b32_e32 v221, 0
	v_mov_b32_e32 v222, 0
	v_mov_b32_e32 v223, 0
	v_mov_b32_e32 v224, 0
	v_mov_b32_e32 v225, 0
	v_readfirstlane_b32 s21, v92
	v_add_u32_e32 v242, v89, v93
	v_add_u32_e32 v243, v91, v93
	v_add_u32_e32 v244, v89, v90
	v_add_u32_e32 v245, v91, v90
	s_mov_b32 s0, 0x3ff80
	s_mov_b32 s1, 0
	s_add_i32 m0, s21, 0x8000
	v_lshl_add_u64 v[82:83], v[74:75], 0, s[0:1]
	global_load_lds_dwordx4 v[82:83], off
	s_add_i32 m0, m0, 0x1000
	v_lshl_add_u64 v[82:83], v[76:77], 0, s[0:1]
	global_load_lds_dwordx4 v[82:83], off
	s_add_i32 m0, m0, 0x1000
	v_lshl_add_u64 v[82:83], v[78:79], 0, s[0:1]
	global_load_lds_dwordx4 v[82:83], off
	s_add_i32 m0, m0, 0x1000
	v_lshl_add_u64 v[82:83], v[80:81], 0, s[0:1]
	global_load_lds_dwordx4 v[82:83], off
	s_mov_b64 s[0:1], 0
	s_add_i32 m0, s21, 0xc000
	v_lshl_add_u64 v[82:83], v[66:67], 0, s[0:1]
	global_load_lds_dwordx4 v[82:83], off
	s_add_i32 m0, m0, 0x1000
	v_lshl_add_u64 v[82:83], v[68:69], 0, s[0:1]
	global_load_lds_dwordx4 v[82:83], off
	s_add_i32 m0, m0, 0x1000
	v_lshl_add_u64 v[82:83], v[70:71], 0, s[0:1]
	global_load_lds_dwordx4 v[82:83], off
	s_add_i32 m0, m0, 0x1000
	v_lshl_add_u64 v[82:83], v[72:73], 0, s[0:1]
	global_load_lds_dwordx4 v[82:83], off
